# RWKV scan: per-chunk y reduce-scatter uses DPP bank masks for its first two stages (16 fewer VALU per 16-step chunk)
# speedup vs baseline: 1.0009x; 1.0009x over previous
; DI void phase_scan(const Params& p, char* smem) {
;     ...
;   for (int c = 0; c < NCH; ++c) {
;     if (c + 1 < NCH) SCAN_GLOAD(c + 1);
;     const float* bb = buf + (c & 1) * BSZ;
;     const int rowbase = scan_row(b, dir, c * CH);
;     const int rstep = dir ? -1 : 1;
;     const float* bl = bb + kq * 4;
;     const float* bv = bb + 5 * CH * 64 + wave * 4 + rg;
;     float4 fwv[3], fkv[3], fbv[3], fav[3], frv[3]; float vvv[3];
; #pragma unroll
;     for (int q = 0; q < 2; ++q) {
;       fwv[q] = *(const float4*)(bl + 0 * CH * 64 + q * 64); fkv[q] = *(const float4*)(bl + 1 * CH * 64 + q * 64); fbv[q] = *(const float4*)(bl + 2 * CH * 64 + q * 64);
;       fav[q] = *(const float4*)(bl + 3 * CH * 64 + q * 64); frv[q] = *(const float4*)(bl + 4 * CH * 64 + q * 64); vvv[q] = bv[q * 16];
;     }
;     float ysel = 0.f, ypart = 0.f;
; #pragma unroll
;     for (int s = 0; s < CH; ++s) {
;       const float4 fw = fwv[s % 3], fk = fkv[s % 3], fb = fbv[s % 3], fa = fav[s % 3], fr = frv[s % 3];
;       const float vv = vvv[s % 3];
;       const float2_t a01 = {fa.x, fa.y}, a23 = {fa.z, fa.w};
;       const float2_t w01 = {fw.x, fw.y}, w23 = {fw.z, fw.w}, k01 = {fk.x, fk.y}, k23 = {fk.z, fk.w}, b01 = {fb.x, fb.y}, b23 = {fb.z, fb.w};
;       const float2_t r01 = {fr.x, fr.y}, r23 = {fr.z, fr.w};
;       const float2_t vv2 = {vv, vv};
;       if (s + 2 < CH) {
;         constexpr int dummy = 0; (void)dummy;
;         const int q = (s + 2) % 3;
;         fwv[q] = *(const float4*)(bl + 0 * CH * 64 + (s + 2) * 64); fkv[q] = *(const float4*)(bl + 1 * CH * 64 + (s + 2) * 64); fbv[q] = *(const float4*)(bl + 2 * CH * 64 + (s + 2) * 64);
;         fav[q] = *(const float4*)(bl + 3 * CH * 64 + (s + 2) * 64); frv[q] = *(const float4*)(bl + 4 * CH * 64 + (s + 2) * 64); vvv[q] = bv[(s + 2) * 16];
;       }
;       float2_t t2 = S01 * a01; t2 = S23 * a23 + t2;
;       const float2_t q01 = S01 * w01 + vv2 * k01, q23 = S23 * w23 + vv2 * k23;
;       float xs = t2.x + t2.y, ys = ypart;
;       xs += __builtin_bit_cast(float, __builtin_amdgcn_update_dpp(0, __builtin_bit_cast(int, xs), 0x128, 0xf, 0xf, false));
;       ys += __builtin_bit_cast(float, __builtin_amdgcn_update_dpp(0, __builtin_bit_cast(int, ys), 0x128, 0xf, 0xf, false));
;       xs += __builtin_bit_cast(float, __builtin_amdgcn_update_dpp(0, __builtin_bit_cast(int, xs), 0x124, 0xf, 0xf, false));
.LBB0_512:
	s_bitcmp1_b32 s96, 0
	s_cselect_b32 s79, 0x5400, 0
	v_lshlrev_b32_e32 v32, 2, v25
	v_lshlrev_b32_e32 v33, 2, v24
	v_add3_u32 v32, s79, v32, v33
	v_add_u32_e32 v32, 0x5000, v32
	v_lshl_or_b32 v31, v2, 2, s79
	ds_read2_b32 v[164:165], v32 offset0:0 offset1:16
	ds_read2_b32 v[166:167], v32 offset0:32 offset1:48
	ds_read2_b32 v[168:169], v32 offset0:64 offset1:80
	ds_read2_b32 v[170:171], v32 offset0:96 offset1:112
	ds_read_b128 v[100:103], v31 offset:0
	ds_read_b128 v[104:107], v31 offset:4096
	ds_read_b128 v[108:111], v31 offset:8192
	ds_read_b128 v[112:115], v31 offset:12288
	ds_read_b128 v[116:119], v31 offset:16384
	ds_read_b128 v[120:123], v31 offset:256
	ds_read_b128 v[124:127], v31 offset:4352
	ds_read_b128 v[128:131], v31 offset:8448
	ds_read_b128 v[132:135], v31 offset:12544
	ds_read_b128 v[136:139], v31 offset:16640
	v_add_u32_e32 v30, v30, v0
	s_add_i32 s96, s96, 1
	s_andn2_b64 vcc, exec, s[46:47]
	s_waitcnt lgkmcnt(5)
	v_pk_mul_f32 v[42:43], v[114:115], v[20:21]
	v_pk_mul_f32 v[46:47], v[102:103], v[20:21]
	v_pk_fma_f32 v[42:43], v[112:113], v[18:19], v[42:43]
	v_pk_mul_f32 v[44:45], v[100:101], v[18:19]
	v_add_f32_e32 v48, v42, v43
	v_pk_fma_f32 v[44:45], v[104:105], v[164:165], v[44:45] op_sel_hi:[1,0,1]
	v_pk_fma_f32 v[46:47], v[106:107], v[164:165], v[46:47] op_sel_hi:[1,0,1]
	v_add_f32_dpp v48, v48, v48 row_ror:8 row_mask:0xf bank_mask:0xf bound_ctrl:1
	ds_read_b128 v[140:143], v31 offset:512
	ds_read_b128 v[144:147], v31 offset:4608
	v_add_f32_dpp v48, v48, v48 row_ror:4 row_mask:0xf bank_mask:0xf bound_ctrl:1
	ds_read_b128 v[148:151], v31 offset:8704
	ds_read_b128 v[152:155], v31 offset:12800
	v_add_f32_dpp v48, v48, v48 row_ror:2 row_mask:0xf bank_mask:0xf bound_ctrl:1
	ds_read_b128 v[156:159], v31 offset:16896
	s_nop 0
	v_add_f32_dpp v48, v48, v48 row_ror:1 row_mask:0xf bank_mask:0xf bound_ctrl:1
	v_pk_fma_f32 v[18:19], v[108:109], v[48:49], v[44:45] op_sel_hi:[1,0,1]
	v_pk_fma_f32 v[20:21], v[110:111], v[48:49], v[46:47] op_sel_hi:[1,0,1]
	s_waitcnt lgkmcnt(5)
	v_pk_mul_f32 v[42:43], v[134:135], v[20:21]
	v_pk_mul_f32 v[46:47], v[122:123], v[20:21]
	v_pk_fma_f32 v[42:43], v[132:133], v[18:19], v[42:43]
	v_pk_mul_f32 v[44:45], v[120:121], v[18:19]
	v_add_f32_e32 v48, v42, v43
	v_pk_fma_f32 v[44:45], v[124:125], v[164:165], v[44:45] op_sel:[0,1,0]
	v_pk_fma_f32 v[46:47], v[126:127], v[164:165], v[46:47] op_sel:[0,1,0]
	v_add_f32_dpp v48, v48, v48 row_ror:8 row_mask:0xf bank_mask:0xf bound_ctrl:1
	v_pk_mul_f32 v[50:51], v[116:117], v[18:19]
	v_pk_fma_f32 v[50:51], v[118:119], v[20:21], v[50:51]
	v_add_f32_dpp v48, v48, v48 row_ror:4 row_mask:0xf bank_mask:0xf bound_ctrl:1
	v_add_f32_e32 v180, v50, v51
	ds_read_b128 v[100:103], v31 offset:768
	v_add_f32_dpp v48, v48, v48 row_ror:2 row_mask:0xf bank_mask:0xf bound_ctrl:1
	ds_read_b128 v[104:107], v31 offset:4864
	ds_read_b128 v[108:111], v31 offset:8960
	v_add_f32_dpp v48, v48, v48 row_ror:1 row_mask:0xf bank_mask:0xf bound_ctrl:1
	ds_read_b128 v[112:115], v31 offset:13056
	ds_read_b128 v[116:119], v31 offset:17152
	v_pk_fma_f32 v[18:19], v[128:129], v[48:49], v[44:45] op_sel_hi:[1,0,1]
	v_pk_fma_f32 v[20:21], v[130:131], v[48:49], v[46:47] op_sel_hi:[1,0,1]
	s_waitcnt lgkmcnt(5)
	v_pk_mul_f32 v[42:43], v[154:155], v[20:21]
	v_pk_mul_f32 v[46:47], v[142:143], v[20:21]
	v_pk_fma_f32 v[42:43], v[152:153], v[18:19], v[42:43]
	v_pk_mul_f32 v[44:45], v[140:141], v[18:19]
	v_add_f32_e32 v48, v42, v43
	v_pk_fma_f32 v[44:45], v[144:145], v[166:167], v[44:45] op_sel_hi:[1,0,1]
	v_pk_fma_f32 v[46:47], v[146:147], v[166:167], v[46:47] op_sel_hi:[1,0,1]
	v_add_f32_dpp v48, v48, v48 row_ror:8 row_mask:0xf bank_mask:0xf bound_ctrl:1
	v_pk_mul_f32 v[50:51], v[136:137], v[18:19]
	v_pk_fma_f32 v[50:51], v[138:139], v[20:21], v[50:51]
	v_add_f32_dpp v48, v48, v48 row_ror:4 row_mask:0xf bank_mask:0xf bound_ctrl:1
	v_add_f32_e32 v181, v50, v51
	ds_read_b128 v[120:123], v31 offset:1024
	v_add_f32_dpp v48, v48, v48 row_ror:2 row_mask:0xf bank_mask:0xf bound_ctrl:1
	ds_read_b128 v[124:127], v31 offset:5120
	ds_read_b128 v[128:131], v31 offset:9216
	v_add_f32_dpp v48, v48, v48 row_ror:1 row_mask:0xf bank_mask:0xf bound_ctrl:1
	ds_read_b128 v[132:135], v31 offset:13312
	ds_read_b128 v[136:139], v31 offset:17408
	ds_read2_b32 v[172:173], v32 offset0:128 offset1:144
	ds_read2_b32 v[174:175], v32 offset0:160 offset1:176
	v_pk_fma_f32 v[18:19], v[148:149], v[48:49], v[44:45] op_sel_hi:[1,0,1]
	v_pk_fma_f32 v[20:21], v[150:151], v[48:49], v[46:47] op_sel_hi:[1,0,1]
	s_waitcnt lgkmcnt(7)
	v_pk_mul_f32 v[42:43], v[114:115], v[20:21]
	v_pk_mul_f32 v[46:47], v[102:103], v[20:21]
	v_pk_fma_f32 v[42:43], v[112:113], v[18:19], v[42:43]
	v_pk_mul_f32 v[44:45], v[100:101], v[18:19]
	v_add_f32_e32 v48, v42, v43
	v_pk_fma_f32 v[44:45], v[104:105], v[166:167], v[44:45] op_sel:[0,1,0]
	v_pk_fma_f32 v[46:47], v[106:107], v[166:167], v[46:47] op_sel:[0,1,0]
	v_add_f32_dpp v48, v48, v48 row_ror:8 row_mask:0xf bank_mask:0xf bound_ctrl:1
	v_pk_mul_f32 v[50:51], v[156:157], v[18:19]
	v_pk_fma_f32 v[50:51], v[158:159], v[20:21], v[50:51]
	v_add_f32_dpp v48, v48, v48 row_ror:4 row_mask:0xf bank_mask:0xf bound_ctrl:1
	v_add_f32_e32 v182, v50, v51
	ds_read_b128 v[140:143], v31 offset:1280
	v_add_f32_dpp v48, v48, v48 row_ror:2 row_mask:0xf bank_mask:0xf bound_ctrl:1
	ds_read_b128 v[144:147], v31 offset:5376
	ds_read_b128 v[148:151], v31 offset:9472
	v_add_f32_dpp v48, v48, v48 row_ror:1 row_mask:0xf bank_mask:0xf bound_ctrl:1
	ds_read_b128 v[152:155], v31 offset:13568
	ds_read_b128 v[156:159], v31 offset:17664
	ds_read2_b32 v[176:177], v32 offset0:192 offset1:208
	ds_read2_b32 v[178:179], v32 offset0:224 offset1:240
	v_pk_fma_f32 v[18:19], v[108:109], v[48:49], v[44:45] op_sel_hi:[1,0,1]
	v_pk_fma_f32 v[20:21], v[110:111], v[48:49], v[46:47] op_sel_hi:[1,0,1]
	s_waitcnt lgkmcnt(9)
; DI void phase_scan(const Params& p, char* smem) {
;     ...
;     for (int s = 0; s < CH; ++s) {
;       const float4 fw = fwv[s % 3], fk = fkv[s % 3], fb = fbv[s % 3], fa = fav[s % 3], fr = frv[s % 3];
;       const float vv = vvv[s % 3];
;       const float2_t a01 = {fa.x, fa.y}, a23 = {fa.z, fa.w};
;       const float2_t w01 = {fw.x, fw.y}, w23 = {fw.z, fw.w}, k01 = {fk.x, fk.y}, k23 = {fk.z, fk.w}, b01 = {fb.x, fb.y}, b23 = {fb.z, fb.w};
;       const float2_t r01 = {fr.x, fr.y}, r23 = {fr.z, fr.w};
;       const float2_t vv2 = {vv, vv};
;       if (s + 2 < CH) {
;         constexpr int dummy = 0; (void)dummy;
;         const int q = (s + 2) % 3;
;         fwv[q] = *(const float4*)(bl + 0 * CH * 64 + (s + 2) * 64); fkv[q] = *(const float4*)(bl + 1 * CH * 64 + (s + 2) * 64); fbv[q] = *(const float4*)(bl + 2 * CH * 64 + (s + 2) * 64);
;         fav[q] = *(const float4*)(bl + 3 * CH * 64 + (s + 2) * 64); frv[q] = *(const float4*)(bl + 4 * CH * 64 + (s + 2) * 64); vvv[q] = bv[(s + 2) * 16];
;       }
;       float2_t t2 = S01 * a01; t2 = S23 * a23 + t2;
;       const float2_t q01 = S01 * w01 + vv2 * k01, q23 = S23 * w23 + vv2 * k23;
;       float xs = t2.x + t2.y, ys = ypart;
;       xs += __builtin_bit_cast(float, __builtin_amdgcn_update_dpp(0, __builtin_bit_cast(int, xs), 0x128, 0xf, 0xf, false));
;       ys += __builtin_bit_cast(float, __builtin_amdgcn_update_dpp(0, __builtin_bit_cast(int, ys), 0x128, 0xf, 0xf, false));
;       xs += __builtin_bit_cast(float, __builtin_amdgcn_update_dpp(0, __builtin_bit_cast(int, xs), 0x124, 0xf, 0xf, false));
;       ys += __builtin_bit_cast(float, __builtin_amdgcn_update_dpp(0, __builtin_bit_cast(int, ys), 0x124, 0xf, 0xf, false));
;       xs += __builtin_bit_cast(float, __builtin_amdgcn_update_dpp(0, __builtin_bit_cast(int, xs), 0x122, 0xf, 0xf, false));
;       ys += __builtin_bit_cast(float, __builtin_amdgcn_update_dpp(0, __builtin_bit_cast(int, ys), 0x122, 0xf, 0xf, false));
;       xs += __builtin_bit_cast(float, __builtin_amdgcn_update_dpp(0, __builtin_bit_cast(int, xs), 0x121, 0xf, 0xf, false));
;       ys += __builtin_bit_cast(float, __builtin_amdgcn_update_dpp(0, __builtin_bit_cast(int, ys), 0x121, 0xf, 0xf, false));
;       if (s > 0) ysel = (kq == s - 1) ? ys : ysel;
;       const float2_t sa2 = {xs, xs};
;       S01 = sa2 * b01 + q01; S23 = sa2 * b23 + q23;
;       float2_t y2 = S01 * r01; y2 = S23 * r23 + y2;
	v_pk_mul_f32 v[42:43], v[134:135], v[20:21]
	v_pk_mul_f32 v[46:47], v[122:123], v[20:21]
	v_pk_fma_f32 v[42:43], v[132:133], v[18:19], v[42:43]
	v_pk_mul_f32 v[44:45], v[120:121], v[18:19]
	v_add_f32_e32 v48, v42, v43
	v_pk_fma_f32 v[44:45], v[124:125], v[168:169], v[44:45] op_sel_hi:[1,0,1]
	v_pk_fma_f32 v[46:47], v[126:127], v[168:169], v[46:47] op_sel_hi:[1,0,1]
	v_add_f32_dpp v48, v48, v48 row_ror:8 row_mask:0xf bank_mask:0xf bound_ctrl:1
	v_pk_mul_f32 v[50:51], v[116:117], v[18:19]
	v_pk_fma_f32 v[50:51], v[118:119], v[20:21], v[50:51]
	v_add_f32_dpp v48, v48, v48 row_ror:4 row_mask:0xf bank_mask:0xf bound_ctrl:1
	v_add_f32_e32 v183, v50, v51
	ds_read_b128 v[100:103], v31 offset:1536
	v_add_f32_dpp v48, v48, v48 row_ror:2 row_mask:0xf bank_mask:0xf bound_ctrl:1
	ds_read_b128 v[104:107], v31 offset:5632
	ds_read_b128 v[108:111], v31 offset:9728
	v_add_f32_dpp v48, v48, v48 row_ror:1 row_mask:0xf bank_mask:0xf bound_ctrl:1
	ds_read_b128 v[112:115], v31 offset:13824
	ds_read_b128 v[116:119], v31 offset:17920
	v_pk_fma_f32 v[18:19], v[128:129], v[48:49], v[44:45] op_sel_hi:[1,0,1]
	v_pk_fma_f32 v[20:21], v[130:131], v[48:49], v[46:47] op_sel_hi:[1,0,1]
	s_waitcnt lgkmcnt(7)
	v_pk_mul_f32 v[42:43], v[154:155], v[20:21]
	v_pk_mul_f32 v[46:47], v[142:143], v[20:21]
	v_pk_fma_f32 v[42:43], v[152:153], v[18:19], v[42:43]
	v_pk_mul_f32 v[44:45], v[140:141], v[18:19]
	v_add_f32_e32 v48, v42, v43
	v_pk_fma_f32 v[44:45], v[144:145], v[168:169], v[44:45] op_sel:[0,1,0]
	v_pk_fma_f32 v[46:47], v[146:147], v[168:169], v[46:47] op_sel:[0,1,0]
	v_add_f32_dpp v48, v48, v48 row_ror:8 row_mask:0xf bank_mask:0xf bound_ctrl:1
	v_pk_mul_f32 v[50:51], v[136:137], v[18:19]
	v_pk_fma_f32 v[50:51], v[138:139], v[20:21], v[50:51]
	v_add_f32_dpp v48, v48, v48 row_ror:4 row_mask:0xf bank_mask:0xf bound_ctrl:1
	v_add_f32_e32 v184, v50, v51
	ds_read_b128 v[120:123], v31 offset:1792
	v_add_f32_dpp v48, v48, v48 row_ror:2 row_mask:0xf bank_mask:0xf bound_ctrl:1
	ds_read_b128 v[124:127], v31 offset:5888
	ds_read_b128 v[128:131], v31 offset:9984
	v_add_f32_dpp v48, v48, v48 row_ror:1 row_mask:0xf bank_mask:0xf bound_ctrl:1
	ds_read_b128 v[132:135], v31 offset:14080
	ds_read_b128 v[136:139], v31 offset:18176
	v_pk_fma_f32 v[18:19], v[148:149], v[48:49], v[44:45] op_sel_hi:[1,0,1]
	v_pk_fma_f32 v[20:21], v[150:151], v[48:49], v[46:47] op_sel_hi:[1,0,1]
	s_waitcnt lgkmcnt(5)
	v_pk_mul_f32 v[42:43], v[114:115], v[20:21]
	v_pk_mul_f32 v[46:47], v[102:103], v[20:21]
	v_pk_fma_f32 v[42:43], v[112:113], v[18:19], v[42:43]
	v_pk_mul_f32 v[44:45], v[100:101], v[18:19]
	v_add_f32_e32 v48, v42, v43
	v_pk_fma_f32 v[44:45], v[104:105], v[170:171], v[44:45] op_sel_hi:[1,0,1]
	v_pk_fma_f32 v[46:47], v[106:107], v[170:171], v[46:47] op_sel_hi:[1,0,1]
	v_add_f32_dpp v48, v48, v48 row_ror:8 row_mask:0xf bank_mask:0xf bound_ctrl:1
	v_pk_mul_f32 v[50:51], v[156:157], v[18:19]
	v_pk_fma_f32 v[50:51], v[158:159], v[20:21], v[50:51]
	v_add_f32_dpp v48, v48, v48 row_ror:4 row_mask:0xf bank_mask:0xf bound_ctrl:1
	v_add_f32_e32 v185, v50, v51
	ds_read_b128 v[140:143], v31 offset:2048
	v_add_f32_dpp v48, v48, v48 row_ror:2 row_mask:0xf bank_mask:0xf bound_ctrl:1
	ds_read_b128 v[144:147], v31 offset:6144
	ds_read_b128 v[148:151], v31 offset:10240
	v_add_f32_dpp v48, v48, v48 row_ror:1 row_mask:0xf bank_mask:0xf bound_ctrl:1
	ds_read_b128 v[152:155], v31 offset:14336
	ds_read_b128 v[156:159], v31 offset:18432
	v_pk_fma_f32 v[18:19], v[108:109], v[48:49], v[44:45] op_sel_hi:[1,0,1]
	v_pk_fma_f32 v[20:21], v[110:111], v[48:49], v[46:47] op_sel_hi:[1,0,1]
	s_waitcnt lgkmcnt(5)
	v_pk_mul_f32 v[42:43], v[134:135], v[20:21]
	v_pk_mul_f32 v[46:47], v[122:123], v[20:21]
	v_pk_fma_f32 v[42:43], v[132:133], v[18:19], v[42:43]
	v_pk_mul_f32 v[44:45], v[120:121], v[18:19]
	v_add_f32_e32 v48, v42, v43
	v_pk_fma_f32 v[44:45], v[124:125], v[170:171], v[44:45] op_sel:[0,1,0]
	v_pk_fma_f32 v[46:47], v[126:127], v[170:171], v[46:47] op_sel:[0,1,0]
	v_add_f32_dpp v48, v48, v48 row_ror:8 row_mask:0xf bank_mask:0xf bound_ctrl:1
	v_pk_mul_f32 v[50:51], v[116:117], v[18:19]
	v_pk_fma_f32 v[50:51], v[118:119], v[20:21], v[50:51]
	v_add_f32_dpp v48, v48, v48 row_ror:4 row_mask:0xf bank_mask:0xf bound_ctrl:1
	v_add_f32_e32 v186, v50, v51
	ds_read_b128 v[100:103], v31 offset:2304
	v_add_f32_dpp v48, v48, v48 row_ror:2 row_mask:0xf bank_mask:0xf bound_ctrl:1
	ds_read_b128 v[104:107], v31 offset:6400
	ds_read_b128 v[108:111], v31 offset:10496
	v_add_f32_dpp v48, v48, v48 row_ror:1 row_mask:0xf bank_mask:0xf bound_ctrl:1
	ds_read_b128 v[112:115], v31 offset:14592
	ds_read_b128 v[116:119], v31 offset:18688
	v_pk_fma_f32 v[18:19], v[128:129], v[48:49], v[44:45] op_sel_hi:[1,0,1]
	v_pk_fma_f32 v[20:21], v[130:131], v[48:49], v[46:47] op_sel_hi:[1,0,1]
	s_waitcnt lgkmcnt(5)
	v_pk_mul_f32 v[42:43], v[154:155], v[20:21]
	v_pk_mul_f32 v[46:47], v[142:143], v[20:21]
	v_pk_fma_f32 v[42:43], v[152:153], v[18:19], v[42:43]
	v_pk_mul_f32 v[44:45], v[140:141], v[18:19]
	v_add_f32_e32 v48, v42, v43
	v_pk_fma_f32 v[44:45], v[144:145], v[172:173], v[44:45] op_sel_hi:[1,0,1]
	v_pk_fma_f32 v[46:47], v[146:147], v[172:173], v[46:47] op_sel_hi:[1,0,1]
	v_add_f32_dpp v48, v48, v48 row_ror:8 row_mask:0xf bank_mask:0xf bound_ctrl:1
	v_pk_mul_f32 v[50:51], v[136:137], v[18:19]
	v_pk_fma_f32 v[50:51], v[138:139], v[20:21], v[50:51]
	v_add_f32_dpp v48, v48, v48 row_ror:4 row_mask:0xf bank_mask:0xf bound_ctrl:1
	v_add_f32_e32 v187, v50, v51
	ds_read_b128 v[120:123], v31 offset:2560
	v_add_f32_dpp v48, v48, v48 row_ror:2 row_mask:0xf bank_mask:0xf bound_ctrl:1
	ds_read_b128 v[124:127], v31 offset:6656
	ds_read_b128 v[128:131], v31 offset:10752
	v_add_f32_dpp v48, v48, v48 row_ror:1 row_mask:0xf bank_mask:0xf bound_ctrl:1
	ds_read_b128 v[132:135], v31 offset:14848
	ds_read_b128 v[136:139], v31 offset:18944
	v_pk_fma_f32 v[18:19], v[148:149], v[48:49], v[44:45] op_sel_hi:[1,0,1]
	v_pk_fma_f32 v[20:21], v[150:151], v[48:49], v[46:47] op_sel_hi:[1,0,1]
	s_waitcnt lgkmcnt(5)
; DI void phase_scan(const Params& p, char* smem) {
;     ...
;     for (int s = 0; s < CH; ++s) {
;       const float4 fw = fwv[s % 3], fk = fkv[s % 3], fb = fbv[s % 3], fa = fav[s % 3], fr = frv[s % 3];
;       const float vv = vvv[s % 3];
;       const float2_t a01 = {fa.x, fa.y}, a23 = {fa.z, fa.w};
;       const float2_t w01 = {fw.x, fw.y}, w23 = {fw.z, fw.w}, k01 = {fk.x, fk.y}, k23 = {fk.z, fk.w}, b01 = {fb.x, fb.y}, b23 = {fb.z, fb.w};
;       const float2_t r01 = {fr.x, fr.y}, r23 = {fr.z, fr.w};
;       const float2_t vv2 = {vv, vv};
;       if (s + 2 < CH) {
;         constexpr int dummy = 0; (void)dummy;
;         const int q = (s + 2) % 3;
;         fwv[q] = *(const float4*)(bl + 0 * CH * 64 + (s + 2) * 64); fkv[q] = *(const float4*)(bl + 1 * CH * 64 + (s + 2) * 64); fbv[q] = *(const float4*)(bl + 2 * CH * 64 + (s + 2) * 64);
;         fav[q] = *(const float4*)(bl + 3 * CH * 64 + (s + 2) * 64); frv[q] = *(const float4*)(bl + 4 * CH * 64 + (s + 2) * 64); vvv[q] = bv[(s + 2) * 16];
;       }
;       float2_t t2 = S01 * a01; t2 = S23 * a23 + t2;
;       const float2_t q01 = S01 * w01 + vv2 * k01, q23 = S23 * w23 + vv2 * k23;
;       float xs = t2.x + t2.y, ys = ypart;
;       xs += __builtin_bit_cast(float, __builtin_amdgcn_update_dpp(0, __builtin_bit_cast(int, xs), 0x128, 0xf, 0xf, false));
;       ys += __builtin_bit_cast(float, __builtin_amdgcn_update_dpp(0, __builtin_bit_cast(int, ys), 0x128, 0xf, 0xf, false));
;       xs += __builtin_bit_cast(float, __builtin_amdgcn_update_dpp(0, __builtin_bit_cast(int, xs), 0x124, 0xf, 0xf, false));
;       ys += __builtin_bit_cast(float, __builtin_amdgcn_update_dpp(0, __builtin_bit_cast(int, ys), 0x124, 0xf, 0xf, false));
;       xs += __builtin_bit_cast(float, __builtin_amdgcn_update_dpp(0, __builtin_bit_cast(int, xs), 0x122, 0xf, 0xf, false));
;       ys += __builtin_bit_cast(float, __builtin_amdgcn_update_dpp(0, __builtin_bit_cast(int, ys), 0x122, 0xf, 0xf, false));
;       xs += __builtin_bit_cast(float, __builtin_amdgcn_update_dpp(0, __builtin_bit_cast(int, xs), 0x121, 0xf, 0xf, false));
;       ys += __builtin_bit_cast(float, __builtin_amdgcn_update_dpp(0, __builtin_bit_cast(int, ys), 0x121, 0xf, 0xf, false));
;       if (s > 0) ysel = (kq == s - 1) ? ys : ysel;
;       const float2_t sa2 = {xs, xs};
;       S01 = sa2 * b01 + q01; S23 = sa2 * b23 + q23;
;       float2_t y2 = S01 * r01; y2 = S23 * r23 + y2;
	v_pk_mul_f32 v[42:43], v[114:115], v[20:21]
	v_pk_mul_f32 v[46:47], v[102:103], v[20:21]
	v_pk_fma_f32 v[42:43], v[112:113], v[18:19], v[42:43]
	v_pk_mul_f32 v[44:45], v[100:101], v[18:19]
	v_add_f32_e32 v48, v42, v43
	v_pk_fma_f32 v[44:45], v[104:105], v[172:173], v[44:45] op_sel:[0,1,0]
	v_pk_fma_f32 v[46:47], v[106:107], v[172:173], v[46:47] op_sel:[0,1,0]
	v_add_f32_dpp v48, v48, v48 row_ror:8 row_mask:0xf bank_mask:0xf bound_ctrl:1
	v_pk_mul_f32 v[50:51], v[156:157], v[18:19]
	v_pk_fma_f32 v[50:51], v[158:159], v[20:21], v[50:51]
	v_add_f32_dpp v48, v48, v48 row_ror:4 row_mask:0xf bank_mask:0xf bound_ctrl:1
	v_add_f32_e32 v188, v50, v51
	ds_read_b128 v[140:143], v31 offset:2816
	v_add_f32_dpp v48, v48, v48 row_ror:2 row_mask:0xf bank_mask:0xf bound_ctrl:1
	ds_read_b128 v[144:147], v31 offset:6912
	ds_read_b128 v[148:151], v31 offset:11008
	v_add_f32_dpp v48, v48, v48 row_ror:1 row_mask:0xf bank_mask:0xf bound_ctrl:1
	ds_read_b128 v[152:155], v31 offset:15104
	ds_read_b128 v[156:159], v31 offset:19200
	v_pk_fma_f32 v[18:19], v[108:109], v[48:49], v[44:45] op_sel_hi:[1,0,1]
	v_pk_fma_f32 v[20:21], v[110:111], v[48:49], v[46:47] op_sel_hi:[1,0,1]
	s_waitcnt lgkmcnt(5)
	v_pk_mul_f32 v[42:43], v[134:135], v[20:21]
	v_pk_mul_f32 v[46:47], v[122:123], v[20:21]
	v_pk_fma_f32 v[42:43], v[132:133], v[18:19], v[42:43]
	v_pk_mul_f32 v[44:45], v[120:121], v[18:19]
	v_add_f32_e32 v48, v42, v43
	v_pk_fma_f32 v[44:45], v[124:125], v[174:175], v[44:45] op_sel_hi:[1,0,1]
	v_pk_fma_f32 v[46:47], v[126:127], v[174:175], v[46:47] op_sel_hi:[1,0,1]
	v_add_f32_dpp v48, v48, v48 row_ror:8 row_mask:0xf bank_mask:0xf bound_ctrl:1
	v_pk_mul_f32 v[50:51], v[116:117], v[18:19]
	v_pk_fma_f32 v[50:51], v[118:119], v[20:21], v[50:51]
	v_add_f32_dpp v48, v48, v48 row_ror:4 row_mask:0xf bank_mask:0xf bound_ctrl:1
	v_add_f32_e32 v189, v50, v51
	ds_read_b128 v[100:103], v31 offset:3072
	v_add_f32_dpp v48, v48, v48 row_ror:2 row_mask:0xf bank_mask:0xf bound_ctrl:1
	ds_read_b128 v[104:107], v31 offset:7168
	ds_read_b128 v[108:111], v31 offset:11264
	v_add_f32_dpp v48, v48, v48 row_ror:1 row_mask:0xf bank_mask:0xf bound_ctrl:1
	ds_read_b128 v[112:115], v31 offset:15360
	ds_read_b128 v[116:119], v31 offset:19456
	v_pk_fma_f32 v[18:19], v[128:129], v[48:49], v[44:45] op_sel_hi:[1,0,1]
	v_pk_fma_f32 v[20:21], v[130:131], v[48:49], v[46:47] op_sel_hi:[1,0,1]
	s_waitcnt lgkmcnt(5)
	v_pk_mul_f32 v[42:43], v[154:155], v[20:21]
	v_pk_mul_f32 v[46:47], v[142:143], v[20:21]
	v_pk_fma_f32 v[42:43], v[152:153], v[18:19], v[42:43]
	v_pk_mul_f32 v[44:45], v[140:141], v[18:19]
	v_add_f32_e32 v48, v42, v43
	v_pk_fma_f32 v[44:45], v[144:145], v[174:175], v[44:45] op_sel:[0,1,0]
	v_pk_fma_f32 v[46:47], v[146:147], v[174:175], v[46:47] op_sel:[0,1,0]
	v_add_f32_dpp v48, v48, v48 row_ror:8 row_mask:0xf bank_mask:0xf bound_ctrl:1
	v_pk_mul_f32 v[50:51], v[136:137], v[18:19]
	v_pk_fma_f32 v[50:51], v[138:139], v[20:21], v[50:51]
	v_add_f32_dpp v48, v48, v48 row_ror:4 row_mask:0xf bank_mask:0xf bound_ctrl:1
	v_add_f32_e32 v190, v50, v51
	ds_read_b128 v[120:123], v31 offset:3328
	v_add_f32_dpp v48, v48, v48 row_ror:2 row_mask:0xf bank_mask:0xf bound_ctrl:1
	ds_read_b128 v[124:127], v31 offset:7424
	ds_read_b128 v[128:131], v31 offset:11520
	v_add_f32_dpp v48, v48, v48 row_ror:1 row_mask:0xf bank_mask:0xf bound_ctrl:1
	ds_read_b128 v[132:135], v31 offset:15616
	ds_read_b128 v[136:139], v31 offset:19712
	v_pk_fma_f32 v[18:19], v[148:149], v[48:49], v[44:45] op_sel_hi:[1,0,1]
	v_pk_fma_f32 v[20:21], v[150:151], v[48:49], v[46:47] op_sel_hi:[1,0,1]
	s_waitcnt lgkmcnt(5)
	v_pk_mul_f32 v[42:43], v[114:115], v[20:21]
	v_pk_mul_f32 v[46:47], v[102:103], v[20:21]
	v_pk_fma_f32 v[42:43], v[112:113], v[18:19], v[42:43]
	v_pk_mul_f32 v[44:45], v[100:101], v[18:19]
	v_add_f32_e32 v48, v42, v43
	v_pk_fma_f32 v[44:45], v[104:105], v[176:177], v[44:45] op_sel_hi:[1,0,1]
	v_pk_fma_f32 v[46:47], v[106:107], v[176:177], v[46:47] op_sel_hi:[1,0,1]
	v_add_f32_dpp v48, v48, v48 row_ror:8 row_mask:0xf bank_mask:0xf bound_ctrl:1
	v_pk_mul_f32 v[50:51], v[156:157], v[18:19]
	v_pk_fma_f32 v[50:51], v[158:159], v[20:21], v[50:51]
	v_add_f32_dpp v48, v48, v48 row_ror:4 row_mask:0xf bank_mask:0xf bound_ctrl:1
	v_add_f32_e32 v191, v50, v51
	ds_read_b128 v[140:143], v31 offset:3584
	v_add_f32_dpp v48, v48, v48 row_ror:2 row_mask:0xf bank_mask:0xf bound_ctrl:1
	ds_read_b128 v[144:147], v31 offset:7680
	ds_read_b128 v[148:151], v31 offset:11776
	v_add_f32_dpp v48, v48, v48 row_ror:1 row_mask:0xf bank_mask:0xf bound_ctrl:1
	ds_read_b128 v[152:155], v31 offset:15872
	ds_read_b128 v[156:159], v31 offset:19968
	v_pk_fma_f32 v[18:19], v[108:109], v[48:49], v[44:45] op_sel_hi:[1,0,1]
	v_pk_fma_f32 v[20:21], v[110:111], v[48:49], v[46:47] op_sel_hi:[1,0,1]
	s_waitcnt lgkmcnt(5)
	v_pk_mul_f32 v[42:43], v[134:135], v[20:21]
	v_pk_mul_f32 v[46:47], v[122:123], v[20:21]
	v_pk_fma_f32 v[42:43], v[132:133], v[18:19], v[42:43]
	v_pk_mul_f32 v[44:45], v[120:121], v[18:19]
	v_add_f32_e32 v48, v42, v43
	v_pk_fma_f32 v[44:45], v[124:125], v[176:177], v[44:45] op_sel:[0,1,0]
	v_pk_fma_f32 v[46:47], v[126:127], v[176:177], v[46:47] op_sel:[0,1,0]
	v_add_f32_dpp v48, v48, v48 row_ror:8 row_mask:0xf bank_mask:0xf bound_ctrl:1
	v_pk_mul_f32 v[50:51], v[116:117], v[18:19]
	v_pk_fma_f32 v[50:51], v[118:119], v[20:21], v[50:51]
	v_add_f32_dpp v48, v48, v48 row_ror:4 row_mask:0xf bank_mask:0xf bound_ctrl:1
	v_add_f32_e32 v192, v50, v51
	ds_read_b128 v[100:103], v31 offset:3840
	v_add_f32_dpp v48, v48, v48 row_ror:2 row_mask:0xf bank_mask:0xf bound_ctrl:1
	ds_read_b128 v[104:107], v31 offset:7936
	ds_read_b128 v[108:111], v31 offset:12032
	v_add_f32_dpp v48, v48, v48 row_ror:1 row_mask:0xf bank_mask:0xf bound_ctrl:1
	ds_read_b128 v[112:115], v31 offset:16128
	ds_read_b128 v[116:119], v31 offset:20224
	v_pk_fma_f32 v[18:19], v[128:129], v[48:49], v[44:45] op_sel_hi:[1,0,1]
	v_pk_fma_f32 v[20:21], v[130:131], v[48:49], v[46:47] op_sel_hi:[1,0,1]
	s_waitcnt lgkmcnt(5)
; DI u16 f2bf(float a) { return (u16)(pack2(a, 0.f) & 0xffffu); }
; DI void phase_scan(const Params& p, char* smem) {
;     ...
;       float2_t t2 = S01 * a01; t2 = S23 * a23 + t2;
;       const float2_t q01 = S01 * w01 + vv2 * k01, q23 = S23 * w23 + vv2 * k23;
;       float xs = t2.x + t2.y, ys = ypart;
;       xs += __builtin_bit_cast(float, __builtin_amdgcn_update_dpp(0, __builtin_bit_cast(int, xs), 0x128, 0xf, 0xf, false));
;       ys += __builtin_bit_cast(float, __builtin_amdgcn_update_dpp(0, __builtin_bit_cast(int, ys), 0x128, 0xf, 0xf, false));
;       xs += __builtin_bit_cast(float, __builtin_amdgcn_update_dpp(0, __builtin_bit_cast(int, xs), 0x124, 0xf, 0xf, false));
;       ys += __builtin_bit_cast(float, __builtin_amdgcn_update_dpp(0, __builtin_bit_cast(int, ys), 0x124, 0xf, 0xf, false));
;       xs += __builtin_bit_cast(float, __builtin_amdgcn_update_dpp(0, __builtin_bit_cast(int, xs), 0x122, 0xf, 0xf, false));
;       ys += __builtin_bit_cast(float, __builtin_amdgcn_update_dpp(0, __builtin_bit_cast(int, ys), 0x122, 0xf, 0xf, false));
;       xs += __builtin_bit_cast(float, __builtin_amdgcn_update_dpp(0, __builtin_bit_cast(int, xs), 0x121, 0xf, 0xf, false));
;       ys += __builtin_bit_cast(float, __builtin_amdgcn_update_dpp(0, __builtin_bit_cast(int, ys), 0x121, 0xf, 0xf, false));
;       if (s > 0) ysel = (kq == s - 1) ? ys : ysel;
;       const float2_t sa2 = {xs, xs};
;       S01 = sa2 * b01 + q01; S23 = sa2 * b23 + q23;
;       float2_t y2 = S01 * r01; y2 = S23 * r23 + y2;
;       ypart = y2.x + y2.y;
;     }
;     { const float yl = rowsum16(ypart); ysel = (kq == CH - 1) ? yl : ysel; }
;     Y[(size_t)(rowbase + rstep * kq) * 256 + h * 64 + vrow] = f2bf(ysel);
;     if (c + 1 < NCH) SCAN_LSTORE((c + 1) & 1);
	v_pk_mul_f32 v[42:43], v[154:155], v[20:21]
	v_pk_mul_f32 v[46:47], v[142:143], v[20:21]
	v_pk_fma_f32 v[42:43], v[152:153], v[18:19], v[42:43]
	v_pk_mul_f32 v[44:45], v[140:141], v[18:19]
	v_add_f32_e32 v48, v42, v43
	v_pk_fma_f32 v[44:45], v[144:145], v[178:179], v[44:45] op_sel_hi:[1,0,1]
	v_pk_fma_f32 v[46:47], v[146:147], v[178:179], v[46:47] op_sel_hi:[1,0,1]
	v_add_f32_dpp v48, v48, v48 row_ror:8 row_mask:0xf bank_mask:0xf bound_ctrl:1
	v_pk_mul_f32 v[50:51], v[136:137], v[18:19]
	v_pk_fma_f32 v[50:51], v[138:139], v[20:21], v[50:51]
	v_add_f32_dpp v48, v48, v48 row_ror:4 row_mask:0xf bank_mask:0xf bound_ctrl:1
	v_add_f32_e32 v193, v50, v51
	s_nop 0
	v_add_f32_dpp v48, v48, v48 row_ror:2 row_mask:0xf bank_mask:0xf bound_ctrl:1
	s_nop 1
	v_add_f32_dpp v48, v48, v48 row_ror:1 row_mask:0xf bank_mask:0xf bound_ctrl:1
	v_pk_fma_f32 v[18:19], v[148:149], v[48:49], v[44:45] op_sel_hi:[1,0,1]
	v_pk_fma_f32 v[20:21], v[150:151], v[48:49], v[46:47] op_sel_hi:[1,0,1]
	s_waitcnt lgkmcnt(0)
	v_pk_mul_f32 v[42:43], v[114:115], v[20:21]
	v_pk_mul_f32 v[46:47], v[102:103], v[20:21]
	v_pk_fma_f32 v[42:43], v[112:113], v[18:19], v[42:43]
	v_pk_mul_f32 v[44:45], v[100:101], v[18:19]
	v_add_f32_e32 v48, v42, v43
	v_pk_fma_f32 v[44:45], v[104:105], v[178:179], v[44:45] op_sel:[0,1,0]
	v_pk_fma_f32 v[46:47], v[106:107], v[178:179], v[46:47] op_sel:[0,1,0]
	v_add_f32_dpp v48, v48, v48 row_ror:8 row_mask:0xf bank_mask:0xf bound_ctrl:1
	v_pk_mul_f32 v[50:51], v[156:157], v[18:19]
	v_pk_fma_f32 v[50:51], v[158:159], v[20:21], v[50:51]
	v_add_f32_dpp v48, v48, v48 row_ror:4 row_mask:0xf bank_mask:0xf bound_ctrl:1
	v_add_f32_e32 v194, v50, v51
	s_nop 0
	v_add_f32_dpp v48, v48, v48 row_ror:2 row_mask:0xf bank_mask:0xf bound_ctrl:1
	s_nop 1
	v_add_f32_dpp v48, v48, v48 row_ror:1 row_mask:0xf bank_mask:0xf bound_ctrl:1
	v_pk_fma_f32 v[18:19], v[108:109], v[48:49], v[44:45] op_sel_hi:[1,0,1]
	v_pk_fma_f32 v[20:21], v[110:111], v[48:49], v[46:47] op_sel_hi:[1,0,1]
	v_pk_mul_f32 v[50:51], v[116:117], v[18:19]
	v_pk_fma_f32 v[50:51], v[118:119], v[20:21], v[50:51]
	v_add_f32_e32 v195, v50, v51
	v_and_b32_e32 v52, 8, v2
	v_and_b32_e32 v53, 4, v2
	v_cmp_ne_u32_e64 s[8:9], 0, v52
	v_cmp_ne_u32_e64 s[10:11], 0, v53
	v_add_f32_dpp v60, v180, v180 row_ror:8 row_mask:0xf bank_mask:0x3 bound_ctrl:1
	v_add_f32_dpp v61, v181, v181 row_ror:8 row_mask:0xf bank_mask:0x3 bound_ctrl:1
	v_add_f32_dpp v62, v182, v182 row_ror:8 row_mask:0xf bank_mask:0x3 bound_ctrl:1
	v_add_f32_dpp v63, v183, v183 row_ror:8 row_mask:0xf bank_mask:0x3 bound_ctrl:1
	v_add_f32_dpp v64, v184, v184 row_ror:8 row_mask:0xf bank_mask:0x3 bound_ctrl:1
	v_add_f32_dpp v65, v185, v185 row_ror:8 row_mask:0xf bank_mask:0x3 bound_ctrl:1
	v_add_f32_dpp v66, v186, v186 row_ror:8 row_mask:0xf bank_mask:0x3 bound_ctrl:1
	v_add_f32_dpp v67, v187, v187 row_ror:8 row_mask:0xf bank_mask:0x3 bound_ctrl:1
	v_add_f32_dpp v60, v188, v188 row_ror:8 row_mask:0xf bank_mask:0xc bound_ctrl:1
	v_add_f32_dpp v61, v189, v189 row_ror:8 row_mask:0xf bank_mask:0xc bound_ctrl:1
	v_add_f32_dpp v62, v190, v190 row_ror:8 row_mask:0xf bank_mask:0xc bound_ctrl:1
	v_add_f32_dpp v63, v191, v191 row_ror:8 row_mask:0xf bank_mask:0xc bound_ctrl:1
	v_add_f32_dpp v64, v192, v192 row_ror:8 row_mask:0xf bank_mask:0xc bound_ctrl:1
	v_add_f32_dpp v65, v193, v193 row_ror:8 row_mask:0xf bank_mask:0xc bound_ctrl:1
	v_add_f32_dpp v66, v194, v194 row_ror:8 row_mask:0xf bank_mask:0xc bound_ctrl:1
	v_add_f32_dpp v67, v195, v195 row_ror:8 row_mask:0xf bank_mask:0xc bound_ctrl:1
	v_add_f32_dpp v68, v60, v60 row_half_mirror row_mask:0xf bank_mask:0x5 bound_ctrl:1
	v_add_f32_dpp v69, v61, v61 row_half_mirror row_mask:0xf bank_mask:0x5 bound_ctrl:1
	v_add_f32_dpp v70, v62, v62 row_half_mirror row_mask:0xf bank_mask:0x5 bound_ctrl:1
	v_add_f32_dpp v71, v63, v63 row_half_mirror row_mask:0xf bank_mask:0x5 bound_ctrl:1
	v_add_f32_dpp v68, v64, v64 row_half_mirror row_mask:0xf bank_mask:0xa bound_ctrl:1
	v_add_f32_dpp v69, v65, v65 row_half_mirror row_mask:0xf bank_mask:0xa bound_ctrl:1
	v_add_f32_dpp v70, v66, v66 row_half_mirror row_mask:0xf bank_mask:0xa bound_ctrl:1
	v_add_f32_dpp v71, v67, v67 row_half_mirror row_mask:0xf bank_mask:0xa bound_ctrl:1
	v_cndmask_b32_e64 v52, v70, v68, s[8:9]
	v_cndmask_b32_e64 v53, v68, v70, s[8:9]
	v_cndmask_b32_e64 v54, v71, v69, s[8:9]
	v_cndmask_b32_e64 v55, v69, v71, s[8:9]
	v_add_f32_dpp v72, v52, v53 quad_perm:[3,2,1,0] row_mask:0xf bank_mask:0xf bound_ctrl:1
	v_add_f32_dpp v73, v54, v55 quad_perm:[3,2,1,0] row_mask:0xf bank_mask:0xf bound_ctrl:1
	v_cndmask_b32_e64 v52, v73, v72, s[10:11]
	v_cndmask_b32_e64 v53, v72, v73, s[10:11]
	s_nop 1
	v_add_f32_dpp v31, v52, v53 quad_perm:[1,0,3,2] row_mask:0xf bank_mask:0xf bound_ctrl:1
	v_cvt_pk_bf16_f32 v32, v31, s0
	v_ashrrev_i32_e32 v31, 31, v30
	v_lshlrev_b64 v[30:31], 9, v[30:31]
	v_lshl_add_u64 v[30:31], v[16:17], 0, v[30:31]
	flat_store_short v[30:31], v32
	s_cbranch_vccnz .LBB0_507
	s_bitcmp1_b32 s96, 0
	s_cselect_b32 s46, 0x5400, 0
	s_waitcnt vmcnt(0)
	v_lshlrev_b32_e32 v30, 16, v4
	v_and_b32_e32 v31, 0xffff0000, v4
	v_lshlrev_b32_e32 v32, 16, v5
	v_and_b32_e32 v33, 0xffff0000, v5
	v_add_u32_e32 v34, s46, v26
	v_pk_add_f32 v[30:31], v[30:31], 1.0 op_sel_hi:[1,0] neg_lo:[1,0] neg_hi:[1,0]
	v_pk_add_f32 v[32:33], v[32:33], 1.0 op_sel_hi:[1,0] neg_lo:[1,0] neg_hi:[1,0]
	ds_write_b128 v34, v[30:33]
	v_lshlrev_b32_e32 v30, 16, v6
	v_and_b32_e32 v31, 0xffff0000, v6
	v_lshlrev_b32_e32 v32, 16, v7
	v_and_b32_e32 v33, 0xffff0000, v7
	ds_write_b128 v34, v[30:33] offset:4096
	v_lshlrev_b32_e32 v30, 16, v8
	v_and_b32_e32 v31, 0xffff0000, v8
	v_lshlrev_b32_e32 v32, 16, v9
	v_and_b32_e32 v33, 0xffff0000, v9
	ds_write_b128 v34, v[30:33] offset:8192
	v_lshlrev_b32_e32 v30, 16, v10
	v_and_b32_e32 v31, 0xffff0000, v10
	v_lshlrev_b32_e32 v32, 16, v11
	v_and_b32_e32 v33, 0xffff0000, v11
	ds_write_b128 v34, v[30:33] offset:12288
	v_lshlrev_b32_e32 v30, 16, v12
	v_and_b32_e32 v31, 0xffff0000, v12
	v_lshlrev_b32_e32 v32, 16, v13
	v_and_b32_e32 v33, 0xffff0000, v13
	ds_write_b128 v34, v[30:33] offset:16384
	v_lshlrev_b32_e32 v30, 16, v27
	v_add_u32_e32 v31, s46, v28
	ds_write_b32 v31, v30 offset:20480
	s_branch .LBB0_507
